# also pair the K-projection row stores in the kv loop into dwordx4 (permlane16_swap)
# baseline (speedup 1.0000x reference)
; __device__ __forceinline__ unsigned pk2(float lo, float hi) { unsigned r; asm("v_cvt_pk_bf16_f32 %0, %1, %2" : "=v"(r) : "v"(lo), "v"(hi)); return r; }
; __device__ __forceinline__ void mixer_chunk(KP p, LAS unsigned char* lds, int l, int chunk) {
;     ...
; #pragma unroll
;         for (int mt = 0; mt < 8; ++mt) {
;             const float rs = RSK[16 * mt + fr]; const int spos = s0 + 16 * mt + fr;
; #pragma unroll
;             for (int n = 0; n < 2; ++n) {
;                 const f32x4 a = acc[mt][n] * rs; const unsigned p0 = pk2(a[0], a[1]), p1 = pk2(a[2], a[3]);
;                 if ((w & 1) == 0) { u32x2 o; o.x = p0; o.y = p1; *(u32x2*)((bf16_t*)(ws + OFF_K) + ((size_t)(bidx * 4 + head) * SEQ + spos) * 96 + 16 * (2 * pz + n) + 4 * fq) = o; }
.LBB0_322:
	s_andn2_b64 vcc, exec, s[6:7]
	s_cbranch_vccnz .LBB0_324
	v_lshl_add_u64 v[108:109], s[18:19], 1, v[68:69]
	s_nop 1
	v_mov_b32_e32 v244, v102
	v_mov_b32_e32 v245, v103
	v_mov_b32_e32 v248, v108
	v_mov_b32_e32 v249, v109

; __device__ __forceinline__ unsigned pk2(float lo, float hi) { unsigned r; asm("v_cvt_pk_bf16_f32 %0, %1, %2" : "=v"(r) : "v"(lo), "v"(hi)); return r; }
; __device__ __forceinline__ void mixer_chunk(KP p, LAS unsigned char* lds, int l, int chunk) {
;     ...
; #pragma unroll
;         for (int mt = 0; mt < 8; ++mt) {
;             const float rs = RSK[16 * mt + fr]; const int spos = s0 + 16 * mt + fr;
; #pragma unroll
;             for (int n = 0; n < 2; ++n) {
;                 const f32x4 a = acc[mt][n] * rs; const unsigned p0 = pk2(a[0], a[1]), p1 = pk2(a[2], a[3]);
;                 if ((w & 1) == 0) { u32x2 o; o.x = p0; o.y = p1; *(u32x2*)((bf16_t*)(ws + OFF_K) + ((size_t)(bidx * 4 + head) * SEQ + spos) * 96 + 16 * (2 * pz + n) + 4 * fq) = o; }
.LBB0_326:
	s_andn2_b64 vcc, exec, s[6:7]
	s_cbranch_vccnz .LBB0_328
	v_lshl_add_u64 v[100:101], s[18:19], 1, v[68:69]
	v_mov_b32_e32 v246, v60
	v_mov_b32_e32 v247, v61
	v_bfe_u32 v250, v193, 4, 1
	v_mul_u32_u24_e32 v250, 24, v250
	v_add_co_u32_e64 v248, s[98:99], v250, v248
	s_nop 1
	v_addc_co_u32_e64 v249, s[98:99], 0, v249, s[98:99]
	v_permlane16_swap_b32_e32 v244, v246
	v_permlane16_swap_b32_e32 v245, v247
	global_store_dwordx4 v[248:249], v[244:247], off

; __device__ __forceinline__ unsigned pk2(float lo, float hi) { unsigned r; asm("v_cvt_pk_bf16_f32 %0, %1, %2" : "=v"(r) : "v"(lo), "v"(hi)); return r; }
; __device__ __forceinline__ void mixer_chunk(KP p, LAS unsigned char* lds, int l, int chunk) {
;     ...
; #pragma unroll
;         for (int mt = 0; mt < 8; ++mt) {
;             const float rs = RSK[16 * mt + fr]; const int spos = s0 + 16 * mt + fr;
; #pragma unroll
;             for (int n = 0; n < 2; ++n) {
;                 const f32x4 a = acc[mt][n] * rs; const unsigned p0 = pk2(a[0], a[1]), p1 = pk2(a[2], a[3]);
;                 if ((w & 1) == 0) { u32x2 o; o.x = p0; o.y = p1; *(u32x2*)((bf16_t*)(ws + OFF_K) + ((size_t)(bidx * 4 + head) * SEQ + spos) * 96 + 16 * (2 * pz + n) + 4 * fq) = o; }
.LBB0_330:
	s_andn2_b64 vcc, exec, s[6:7]
	s_cbranch_vccnz .LBB0_332
	v_lshl_add_u64 v[56:57], s[18:19], 1, v[70:71]
	s_nop 1
	v_mov_b32_e32 v244, v54
	v_mov_b32_e32 v245, v55
	v_mov_b32_e32 v248, v56
	v_mov_b32_e32 v249, v57

; __device__ __forceinline__ unsigned pk2(float lo, float hi) { unsigned r; asm("v_cvt_pk_bf16_f32 %0, %1, %2" : "=v"(r) : "v"(lo), "v"(hi)); return r; }
; __device__ __forceinline__ void mixer_chunk(KP p, LAS unsigned char* lds, int l, int chunk) {
;     ...
; #pragma unroll
;         for (int mt = 0; mt < 8; ++mt) {
;             const float rs = RSK[16 * mt + fr]; const int spos = s0 + 16 * mt + fr;
; #pragma unroll
;             for (int n = 0; n < 2; ++n) {
;                 const f32x4 a = acc[mt][n] * rs; const unsigned p0 = pk2(a[0], a[1]), p1 = pk2(a[2], a[3]);
;                 if ((w & 1) == 0) { u32x2 o; o.x = p0; o.y = p1; *(u32x2*)((bf16_t*)(ws + OFF_K) + ((size_t)(bidx * 4 + head) * SEQ + spos) * 96 + 16 * (2 * pz + n) + 4 * fq) = o; }
.LBB0_334:
	s_andn2_b64 vcc, exec, s[6:7]
	s_cbranch_vccnz .LBB0_336
	v_lshl_add_u64 v[52:53], s[18:19], 1, v[70:71]
	v_mov_b32_e32 v246, v50
	v_mov_b32_e32 v247, v51
	v_bfe_u32 v250, v193, 4, 1
	v_mul_u32_u24_e32 v250, 24, v250
	v_add_co_u32_e64 v248, s[98:99], v250, v248
	s_nop 1
	v_addc_co_u32_e64 v249, s[98:99], 0, v249, s[98:99]
	v_permlane16_swap_b32_e32 v244, v246
	v_permlane16_swap_b32_e32 v245, v247
	global_store_dwordx4 v[248:249], v[244:247], off

; __device__ __forceinline__ unsigned pk2(float lo, float hi) { unsigned r; asm("v_cvt_pk_bf16_f32 %0, %1, %2" : "=v"(r) : "v"(lo), "v"(hi)); return r; }
; __device__ __forceinline__ void mixer_chunk(KP p, LAS unsigned char* lds, int l, int chunk) {
;     ...
; #pragma unroll
;         for (int mt = 0; mt < 8; ++mt) {
;             const float rs = RSK[16 * mt + fr]; const int spos = s0 + 16 * mt + fr;
; #pragma unroll
;             for (int n = 0; n < 2; ++n) {
;                 const f32x4 a = acc[mt][n] * rs; const unsigned p0 = pk2(a[0], a[1]), p1 = pk2(a[2], a[3]);
;                 if ((w & 1) == 0) { u32x2 o; o.x = p0; o.y = p1; *(u32x2*)((bf16_t*)(ws + OFF_K) + ((size_t)(bidx * 4 + head) * SEQ + spos) * 96 + 16 * (2 * pz + n) + 4 * fq) = o; }
.LBB0_338:
	s_andn2_b64 vcc, exec, s[6:7]
	s_cbranch_vccnz .LBB0_340
	v_lshl_add_u64 v[48:49], s[18:19], 1, v[72:73]
	s_nop 1
	v_mov_b32_e32 v244, v46
	v_mov_b32_e32 v245, v47
	v_mov_b32_e32 v248, v48
	v_mov_b32_e32 v249, v49

; __device__ __forceinline__ unsigned pk2(float lo, float hi) { unsigned r; asm("v_cvt_pk_bf16_f32 %0, %1, %2" : "=v"(r) : "v"(lo), "v"(hi)); return r; }
; __device__ __forceinline__ void mixer_chunk(KP p, LAS unsigned char* lds, int l, int chunk) {
;     ...
; #pragma unroll
;         for (int mt = 0; mt < 8; ++mt) {
;             const float rs = RSK[16 * mt + fr]; const int spos = s0 + 16 * mt + fr;
; #pragma unroll
;             for (int n = 0; n < 2; ++n) {
;                 const f32x4 a = acc[mt][n] * rs; const unsigned p0 = pk2(a[0], a[1]), p1 = pk2(a[2], a[3]);
;                 if ((w & 1) == 0) { u32x2 o; o.x = p0; o.y = p1; *(u32x2*)((bf16_t*)(ws + OFF_K) + ((size_t)(bidx * 4 + head) * SEQ + spos) * 96 + 16 * (2 * pz + n) + 4 * fq) = o; }
.LBB0_342:
	s_andn2_b64 vcc, exec, s[6:7]
	s_cbranch_vccnz .LBB0_344
	v_lshl_add_u64 v[44:45], s[18:19], 1, v[72:73]
	v_mov_b32_e32 v246, v42
	v_mov_b32_e32 v247, v43
	v_bfe_u32 v250, v193, 4, 1
	v_mul_u32_u24_e32 v250, 24, v250
	v_add_co_u32_e64 v248, s[98:99], v250, v248
	s_nop 1
	v_addc_co_u32_e64 v249, s[98:99], 0, v249, s[98:99]
	v_permlane16_swap_b32_e32 v244, v246
	v_permlane16_swap_b32_e32 v245, v247
	global_store_dwordx4 v[248:249], v[244:247], off

; __device__ __forceinline__ unsigned pk2(float lo, float hi) { unsigned r; asm("v_cvt_pk_bf16_f32 %0, %1, %2" : "=v"(r) : "v"(lo), "v"(hi)); return r; }
; __device__ __forceinline__ void mixer_chunk(KP p, LAS unsigned char* lds, int l, int chunk) {
;     ...
; #pragma unroll
;         for (int mt = 0; mt < 8; ++mt) {
;             const float rs = RSK[16 * mt + fr]; const int spos = s0 + 16 * mt + fr;
; #pragma unroll
;             for (int n = 0; n < 2; ++n) {
;                 const f32x4 a = acc[mt][n] * rs; const unsigned p0 = pk2(a[0], a[1]), p1 = pk2(a[2], a[3]);
;                 if ((w & 1) == 0) { u32x2 o; o.x = p0; o.y = p1; *(u32x2*)((bf16_t*)(ws + OFF_K) + ((size_t)(bidx * 4 + head) * SEQ + spos) * 96 + 16 * (2 * pz + n) + 4 * fq) = o; }
.LBB0_346:
	s_andn2_b64 vcc, exec, s[6:7]
	s_cbranch_vccnz .LBB0_348
	v_lshl_add_u64 v[40:41], s[18:19], 1, v[74:75]
	s_nop 1
	v_mov_b32_e32 v244, v38
	v_mov_b32_e32 v245, v39
	v_mov_b32_e32 v248, v40
	v_mov_b32_e32 v249, v41

; __device__ __forceinline__ unsigned pk2(float lo, float hi) { unsigned r; asm("v_cvt_pk_bf16_f32 %0, %1, %2" : "=v"(r) : "v"(lo), "v"(hi)); return r; }
; __device__ __forceinline__ void mixer_chunk(KP p, LAS unsigned char* lds, int l, int chunk) {
;     ...
; #pragma unroll
;         for (int mt = 0; mt < 8; ++mt) {
;             const float rs = RSK[16 * mt + fr]; const int spos = s0 + 16 * mt + fr;
; #pragma unroll
;             for (int n = 0; n < 2; ++n) {
;                 const f32x4 a = acc[mt][n] * rs; const unsigned p0 = pk2(a[0], a[1]), p1 = pk2(a[2], a[3]);
;                 if ((w & 1) == 0) { u32x2 o; o.x = p0; o.y = p1; *(u32x2*)((bf16_t*)(ws + OFF_K) + ((size_t)(bidx * 4 + head) * SEQ + spos) * 96 + 16 * (2 * pz + n) + 4 * fq) = o; }
.LBB0_350:
	s_andn2_b64 vcc, exec, s[6:7]
	s_cbranch_vccnz .LBB0_352
	v_lshl_add_u64 v[36:37], s[18:19], 1, v[74:75]
	v_mov_b32_e32 v246, v34
	v_mov_b32_e32 v247, v35
	v_bfe_u32 v250, v193, 4, 1
	v_mul_u32_u24_e32 v250, 24, v250
	v_add_co_u32_e64 v248, s[98:99], v250, v248
	s_nop 1
	v_addc_co_u32_e64 v249, s[98:99], 0, v249, s[98:99]
	v_permlane16_swap_b32_e32 v244, v246
	v_permlane16_swap_b32_e32 v245, v247
	global_store_dwordx4 v[248:249], v[244:247], off

; __device__ __forceinline__ unsigned pk2(float lo, float hi) { unsigned r; asm("v_cvt_pk_bf16_f32 %0, %1, %2" : "=v"(r) : "v"(lo), "v"(hi)); return r; }
; __device__ __forceinline__ void mixer_chunk(KP p, LAS unsigned char* lds, int l, int chunk) {
;     ...
; #pragma unroll
;         for (int mt = 0; mt < 8; ++mt) {
;             const float rs = RSK[16 * mt + fr]; const int spos = s0 + 16 * mt + fr;
; #pragma unroll
;             for (int n = 0; n < 2; ++n) {
;                 const f32x4 a = acc[mt][n] * rs; const unsigned p0 = pk2(a[0], a[1]), p1 = pk2(a[2], a[3]);
;                 if ((w & 1) == 0) { u32x2 o; o.x = p0; o.y = p1; *(u32x2*)((bf16_t*)(ws + OFF_K) + ((size_t)(bidx * 4 + head) * SEQ + spos) * 96 + 16 * (2 * pz + n) + 4 * fq) = o; }
.LBB0_354:
	s_andn2_b64 vcc, exec, s[6:7]
	s_cbranch_vccnz .LBB0_356
	v_lshl_add_u64 v[32:33], s[18:19], 1, v[76:77]
	s_nop 1
	v_mov_b32_e32 v244, v30
	v_mov_b32_e32 v245, v31
	v_mov_b32_e32 v248, v32
	v_mov_b32_e32 v249, v33

; __device__ __forceinline__ unsigned pk2(float lo, float hi) { unsigned r; asm("v_cvt_pk_bf16_f32 %0, %1, %2" : "=v"(r) : "v"(lo), "v"(hi)); return r; }
; __device__ __forceinline__ void mixer_chunk(KP p, LAS unsigned char* lds, int l, int chunk) {
;     ...
; #pragma unroll
;         for (int mt = 0; mt < 8; ++mt) {
;             const float rs = RSK[16 * mt + fr]; const int spos = s0 + 16 * mt + fr;
; #pragma unroll
;             for (int n = 0; n < 2; ++n) {
;                 const f32x4 a = acc[mt][n] * rs; const unsigned p0 = pk2(a[0], a[1]), p1 = pk2(a[2], a[3]);
;                 if ((w & 1) == 0) { u32x2 o; o.x = p0; o.y = p1; *(u32x2*)((bf16_t*)(ws + OFF_K) + ((size_t)(bidx * 4 + head) * SEQ + spos) * 96 + 16 * (2 * pz + n) + 4 * fq) = o; }
.LBB0_358:
	s_andn2_b64 vcc, exec, s[6:7]
	s_cbranch_vccnz .LBB0_360
	v_lshl_add_u64 v[28:29], s[18:19], 1, v[76:77]
	v_mov_b32_e32 v246, v26
	v_mov_b32_e32 v247, v27
	v_bfe_u32 v250, v193, 4, 1
	v_mul_u32_u24_e32 v250, 24, v250
	v_add_co_u32_e64 v248, s[98:99], v250, v248
	s_nop 1
	v_addc_co_u32_e64 v249, s[98:99], 0, v249, s[98:99]
	v_permlane16_swap_b32_e32 v244, v246
	v_permlane16_swap_b32_e32 v245, v247
	global_store_dwordx4 v[248:249], v[244:247], off

; __device__ __forceinline__ unsigned pk2(float lo, float hi) { unsigned r; asm("v_cvt_pk_bf16_f32 %0, %1, %2" : "=v"(r) : "v"(lo), "v"(hi)); return r; }
; __device__ __forceinline__ void mixer_chunk(KP p, LAS unsigned char* lds, int l, int chunk) {
;     ...
; #pragma unroll
;         for (int mt = 0; mt < 8; ++mt) {
;             const float rs = RSK[16 * mt + fr]; const int spos = s0 + 16 * mt + fr;
; #pragma unroll
;             for (int n = 0; n < 2; ++n) {
;                 const f32x4 a = acc[mt][n] * rs; const unsigned p0 = pk2(a[0], a[1]), p1 = pk2(a[2], a[3]);
;                 if ((w & 1) == 0) { u32x2 o; o.x = p0; o.y = p1; *(u32x2*)((bf16_t*)(ws + OFF_K) + ((size_t)(bidx * 4 + head) * SEQ + spos) * 96 + 16 * (2 * pz + n) + 4 * fq) = o; }
.LBB0_362:
	s_andn2_b64 vcc, exec, s[6:7]
	s_cbranch_vccnz .LBB0_364
	v_lshl_add_u64 v[24:25], s[18:19], 1, v[78:79]
	s_nop 1
	v_mov_b32_e32 v244, v22
	v_mov_b32_e32 v245, v23
	v_mov_b32_e32 v248, v24
	v_mov_b32_e32 v249, v25

; __device__ __forceinline__ unsigned pk2(float lo, float hi) { unsigned r; asm("v_cvt_pk_bf16_f32 %0, %1, %2" : "=v"(r) : "v"(lo), "v"(hi)); return r; }
; __device__ __forceinline__ void mixer_chunk(KP p, LAS unsigned char* lds, int l, int chunk) {
;     ...
; #pragma unroll
;         for (int mt = 0; mt < 8; ++mt) {
;             const float rs = RSK[16 * mt + fr]; const int spos = s0 + 16 * mt + fr;
; #pragma unroll
;             for (int n = 0; n < 2; ++n) {
;                 const f32x4 a = acc[mt][n] * rs; const unsigned p0 = pk2(a[0], a[1]), p1 = pk2(a[2], a[3]);
;                 if ((w & 1) == 0) { u32x2 o; o.x = p0; o.y = p1; *(u32x2*)((bf16_t*)(ws + OFF_K) + ((size_t)(bidx * 4 + head) * SEQ + spos) * 96 + 16 * (2 * pz + n) + 4 * fq) = o; }
.LBB0_366:
	s_andn2_b64 vcc, exec, s[6:7]
	s_cbranch_vccnz .LBB0_368
	v_lshl_add_u64 v[20:21], s[18:19], 1, v[78:79]
	v_mov_b32_e32 v246, v18
	v_mov_b32_e32 v247, v19
	v_bfe_u32 v250, v193, 4, 1
	v_mul_u32_u24_e32 v250, 24, v250
	v_add_co_u32_e64 v248, s[98:99], v250, v248
	s_nop 1
	v_addc_co_u32_e64 v249, s[98:99], 0, v249, s[98:99]
	v_permlane16_swap_b32_e32 v244, v246
	v_permlane16_swap_b32_e32 v245, v247
	global_store_dwordx4 v[248:249], v[244:247], off

; __device__ __forceinline__ unsigned pk2(float lo, float hi) { unsigned r; asm("v_cvt_pk_bf16_f32 %0, %1, %2" : "=v"(r) : "v"(lo), "v"(hi)); return r; }
; __device__ __forceinline__ void mixer_chunk(KP p, LAS unsigned char* lds, int l, int chunk) {
;     ...
; #pragma unroll
;         for (int mt = 0; mt < 8; ++mt) {
;             const float rs = RSK[16 * mt + fr]; const int spos = s0 + 16 * mt + fr;
; #pragma unroll
;             for (int n = 0; n < 2; ++n) {
;                 const f32x4 a = acc[mt][n] * rs; const unsigned p0 = pk2(a[0], a[1]), p1 = pk2(a[2], a[3]);
;                 if ((w & 1) == 0) { u32x2 o; o.x = p0; o.y = p1; *(u32x2*)((bf16_t*)(ws + OFF_K) + ((size_t)(bidx * 4 + head) * SEQ + spos) * 96 + 16 * (2 * pz + n) + 4 * fq) = o; }
.LBB0_370:
	s_andn2_b64 vcc, exec, s[6:7]
	s_cbranch_vccnz .LBB0_372
	v_lshl_add_u64 v[16:17], s[18:19], 1, v[80:81]
	s_nop 1
	v_mov_b32_e32 v244, v14
	v_mov_b32_e32 v245, v15
	v_mov_b32_e32 v248, v16
	v_mov_b32_e32 v249, v17

; __device__ __forceinline__ unsigned pk2(float lo, float hi) { unsigned r; asm("v_cvt_pk_bf16_f32 %0, %1, %2" : "=v"(r) : "v"(lo), "v"(hi)); return r; }
; __device__ __forceinline__ void mixer_chunk(KP p, LAS unsigned char* lds, int l, int chunk) {
;     ...
; #pragma unroll
;         for (int mt = 0; mt < 8; ++mt) {
;             const float rs = RSK[16 * mt + fr]; const int spos = s0 + 16 * mt + fr;
; #pragma unroll
;             for (int n = 0; n < 2; ++n) {
;                 const f32x4 a = acc[mt][n] * rs; const unsigned p0 = pk2(a[0], a[1]), p1 = pk2(a[2], a[3]);
;                 if ((w & 1) == 0) { u32x2 o; o.x = p0; o.y = p1; *(u32x2*)((bf16_t*)(ws + OFF_K) + ((size_t)(bidx * 4 + head) * SEQ + spos) * 96 + 16 * (2 * pz + n) + 4 * fq) = o; }
.LBB0_374:
	s_andn2_b64 vcc, exec, s[6:7]
	s_cbranch_vccnz .LBB0_376
	v_lshl_add_u64 v[12:13], s[18:19], 1, v[80:81]
	v_mov_b32_e32 v246, v10
	v_mov_b32_e32 v247, v11
	v_bfe_u32 v250, v193, 4, 1
	v_mul_u32_u24_e32 v250, 24, v250
	v_add_co_u32_e64 v248, s[98:99], v250, v248
	s_nop 1
	v_addc_co_u32_e64 v249, s[98:99], 0, v249, s[98:99]
	v_permlane16_swap_b32_e32 v244, v246
	v_permlane16_swap_b32_e32 v245, v247
	global_store_dwordx4 v[248:249], v[244:247], off

; __device__ __forceinline__ unsigned pk2(float lo, float hi) { unsigned r; asm("v_cvt_pk_bf16_f32 %0, %1, %2" : "=v"(r) : "v"(lo), "v"(hi)); return r; }
; __device__ __forceinline__ void mixer_chunk(KP p, LAS unsigned char* lds, int l, int chunk) {
;     ...
; #pragma unroll
;         for (int mt = 0; mt < 8; ++mt) {
;             const float rs = RSK[16 * mt + fr]; const int spos = s0 + 16 * mt + fr;
; #pragma unroll
;             for (int n = 0; n < 2; ++n) {
;                 const f32x4 a = acc[mt][n] * rs; const unsigned p0 = pk2(a[0], a[1]), p1 = pk2(a[2], a[3]);
;                 if ((w & 1) == 0) { u32x2 o; o.x = p0; o.y = p1; *(u32x2*)((bf16_t*)(ws + OFF_K) + ((size_t)(bidx * 4 + head) * SEQ + spos) * 96 + 16 * (2 * pz + n) + 4 * fq) = o; }
.LBB0_378:
	s_andn2_b64 vcc, exec, s[6:7]
	s_cbranch_vccnz .LBB0_380
	v_lshl_add_u64 v[8:9], s[18:19], 1, v[82:83]
	s_nop 1
	v_mov_b32_e32 v244, v6
	v_mov_b32_e32 v245, v7
	v_mov_b32_e32 v248, v8
	v_mov_b32_e32 v249, v9

; __device__ __forceinline__ unsigned pk2(float lo, float hi) { unsigned r; asm("v_cvt_pk_bf16_f32 %0, %1, %2" : "=v"(r) : "v"(lo), "v"(hi)); return r; }
; __device__ __forceinline__ void mixer_chunk(KP p, LAS unsigned char* lds, int l, int chunk) {
;     ...
; #pragma unroll
;         for (int mt = 0; mt < 8; ++mt) {
;             const float rs = RSK[16 * mt + fr]; const int spos = s0 + 16 * mt + fr;
; #pragma unroll
;             for (int n = 0; n < 2; ++n) {
;                 const f32x4 a = acc[mt][n] * rs; const unsigned p0 = pk2(a[0], a[1]), p1 = pk2(a[2], a[3]);
;                 if ((w & 1) == 0) { u32x2 o; o.x = p0; o.y = p1; *(u32x2*)((bf16_t*)(ws + OFF_K) + ((size_t)(bidx * 4 + head) * SEQ + spos) * 96 + 16 * (2 * pz + n) + 4 * fq) = o; }
.LBB0_382:
	s_andn2_b64 vcc, exec, s[6:7]
	s_cbranch_vccnz .LBB0_319
	v_lshl_add_u64 v[4:5], s[18:19], 1, v[82:83]
	v_mov_b32_e32 v246, v2
	v_mov_b32_e32 v247, v3
	v_bfe_u32 v250, v193, 4, 1
	v_mul_u32_u24_e32 v250, 24, v250
	v_add_co_u32_e64 v248, s[98:99], v250, v248
	s_nop 1
	v_addc_co_u32_e64 v249, s[98:99], 0, v249, s[98:99]
	v_permlane16_swap_b32_e32 v244, v246
	v_permlane16_swap_b32_e32 v245, v247
	global_store_dwordx4 v[248:249], v[244:247], off
	s_branch .LBB0_319
